# grid.sync between weight-prep and prenorm replaced by a copy of the kernel's own XCD-hierarchical barrier (on top of GEMV prefetch rings + G6 epilogue pipeline)
# speedup vs baseline: 1.0214x; 1.0042x over previous
; __device__ __forceinline__ unsigned xb_ld(unsigned* p)              { return __hip_atomic_load(p, __ATOMIC_RELAXED, __HIP_MEMORY_SCOPE_AGENT); }
; __device__ __forceinline__ void xcd_barrier_complete(unsigned* bar, unsigned x, unsigned& nloc, unsigned& nx) {
;     const unsigned G = gridDim.x * gridDim.y * gridDim.z;
;     unsigned sum, cnt, mine, sp = 0u;
;     for (;;) {
;         sum = 0u; cnt = 0u; mine = 0u;
; #pragma unroll
;         for (unsigned j = 0; j < 16; ++j) { const unsigned c = xb_ld(&bar[XB_XCNT(j)]); sum += c; cnt += (c > 0u) ? 1u : 0u; mine = (j == x) ? c : mine; }
;         if (sum == G) break;
;         __builtin_amdgcn_s_sleep(1);
;         if ((++sp & 255u) == 0u) { if (xb_ld(&bar[XB_TMO])) break; if (sp > XB_SPIN_CAP) { atomicAdd(&bar[XB_TMO], 1u); break; } }
;     }
;     nloc = mine > 0u ? mine : 1u; nx = cnt > 0u ? cnt : 1u;
; }
; __device__ __forceinline__ void xcd_barrier(const XcdBarrier& b) {
;     asm volatile("s_waitcnt vmcnt(0)" ::: "memory");
;     __syncthreads();
;     if (threadIdx.x == 0) {
;         unsigned* bar = b.bar;
;         __builtin_amdgcn_s_waitcnt(0);
;         unsigned nloc = b.st[0], nx = b.st[1];
;         if (nloc == 0u) { xcd_barrier_complete(bar, b.x, nloc, nx); b.st[0] = nloc; b.st[1] = nx; }
.LBB0_66:
	s_mov_b32 s98, s10
	s_mov_b32 s99, s11
	s_getreg_b32 s2, hwreg(HW_REG_XCC_ID, 0, 4)
	s_waitcnt vmcnt(0)
	s_barrier
	s_mov_b64 s[0:1], exec
	v_readlane_b32 s4, v251, 12
	v_readlane_b32 s5, v251, 13
	s_and_b64 s[4:5], s[0:1], s[4:5]
	s_mov_b64 exec, s[4:5]
	s_cbranch_execz .Lcg_142
	s_add_i32 s3, 0, 0x23ff0
	v_mov_b32_e32 v0, s3
	s_waitcnt vmcnt(0) expcnt(0) lgkmcnt(0)
	ds_read_b32 v2, v0
	s_add_i32 s3, 0, 0x23ff4
	v_mov_b32_e32 v0, s3
	ds_read_b32 v0, v0
	s_and_b32 s44, s2, 15
	s_waitcnt lgkmcnt(1)
	v_cmp_ne_u32_e32 vcc, 0, v2
	s_cbranch_vccnz .Lcg_106
	v_readlane_b32 s36, v251, 8
	v_readlane_b32 s37, v251, 9
	s_add_u32 s2, s36, 0xc4200
	s_addc_u32 s3, s37, 0
	s_add_u32 s4, s36, 0xc4400
	s_addc_u32 s5, s37, 0
	s_add_u32 s6, s36, 0xc4500
	s_addc_u32 s7, s37, 0
	s_add_u32 s8, s36, 0xc4600
	s_addc_u32 s9, s37, 0
	s_add_u32 s10, s36, 0xc4700
	s_addc_u32 s11, s37, 0
	s_add_u32 s12, s36, 0xc4800
	s_addc_u32 s13, s37, 0
	s_add_u32 s14, s36, 0xc4900
	s_addc_u32 s15, s37, 0
	s_add_u32 s16, s36, 0xc4a00
	s_addc_u32 s17, s37, 0
	s_add_u32 s18, s36, 0xc4b00
	s_addc_u32 s19, s37, 0
	s_add_u32 s20, s36, 0xc4c00
	s_addc_u32 s21, s37, 0
	s_add_u32 s22, s36, 0xc4d00
	s_addc_u32 s23, s37, 0
	s_add_u32 s24, s36, 0xc4e00
	s_addc_u32 s25, s37, 0
	s_add_u32 s26, s36, 0xc4f00
	s_addc_u32 s27, s37, 0
	s_add_u32 s28, s36, 0xc5000
	s_addc_u32 s29, s37, 0
	s_add_u32 s30, s36, 0xc5100
	s_addc_u32 s31, s37, 0
	s_add_u32 s34, s36, 0xc5200
	v_readlane_b32 s39, v251, 11
	s_addc_u32 s35, s37, 0
	v_readlane_b32 s38, v251, 10
	s_mul_i32 s45, s39, s33
	s_add_u32 s36, s36, 0xc5300
	s_mul_i32 s45, s45, s38
	s_addc_u32 s37, s37, 0
	s_mov_b32 s46, 1
	v_mov_b32_e32 v16, 0
	s_branch .Lcg_94

; #define LAS __attribute__((address_space(3)))
; #define FRESH_IDS() int tid = threadIdx.x; asm volatile("" : "+v"(tid)); const int lane = tid & 63, wave = __builtin_amdgcn_readfirstlane(tid >> 6), gw = bx * 8 + wave; (void)lane; (void)gw
; DI void bias2_item(const float* ada, const float* w1, float* bias2, LAS float* scr, int item, int lane) {
;     const int cb = item % 64, kc = item / 64;
; #pragma unroll 4
;     for (int i = 0; i < 64; ++i) { const int idx = i * 64 + lane, k = idx >> 5, b = idx & 31; scr[idx] = ada[(size_t)b * 6144 + 3072 + kc * 128 + k]; }
; __global__ void __launch_bounds__(512, 2) fwd_mega(Args a) {
;     ...
;     { FRESH_IDS(); LAS float* scr = (LAS float*)(lds + wave * 16384);
;       for (int it = gw; it < 512; it += ngw) bias2_item(ada, a.in[17], bias2, scr, it, lane);
.Lcg_142:
	s_or_b64 exec, exec, s[0:1]
	s_waitcnt vmcnt(0) lgkmcnt(0)
	s_mov_b32 s10, s98
	s_mov_b32 s11, s99
	v_readlane_b32 s0, v251, 8
	v_readlane_b32 s1, v251, 9
	s_add_u32 s0, s0, 0x140000
	s_addc_u32 s1, s1, 0
	v_readlane_b32 s2, v251, 10
	v_readlane_b32 s3, v251, 11
	v_writelane_b32 v251, s0, 44
	v_mov_b32_e32 v0, v188
	s_barrier
	v_writelane_b32 v251, s1, 45
	s_nop 0
	v_readfirstlane_b32 s0, v0
	s_ashr_i32 s0, s0, 6
	s_add_i32 s4, s0, s11
	s_cmpk_gt_i32 s4, 0x1ff
	v_and_b32_e32 v16, 63, v0
	s_cbranch_scc1 .LBB0_83
	s_lshl_b32 s0, s0, 14
	v_and_b32_e32 v0, 31, v0
	s_add_i32 s5, s0, 0
	v_mul_u32_u24_e32 v0, 0x1800, v0
	v_readlane_b32 s0, v251, 8
	v_lshlrev_b32_e32 v0, 2, v0
	v_mov_b32_e32 v1, 0
	v_readlane_b32 s1, v251, 9
	v_mov_b32_e32 v5, v16
	v_lshlrev_b32_e32 v6, 2, v16
	v_lshl_add_u64 v[2:3], s[0:1], 0, v[0:1]
	s_mov_b64 s[0:1], 0x3000
	v_lshl_add_u64 v[2:3], v[2:3], 0, s[0:1]
	v_mov_b32_e32 v7, v1
	s_movk_i32 s6, 0x4000
	s_mov_b64 s[0:1], 0x8000
	s_mov_b32 s7, s4
	v_readlane_b32 s2, v251, 10
	v_readlane_b32 s3, v251, 11
